# v28 + grid-barrier spin loops poll without s_sleep (tighter barrier exit latency)
# speedup vs baseline: 1.0007x; 1.0007x over previous
; __global__ void __launch_bounds__(512, 2) mega(Params p) {
;     ...
;     grid.sync();
.LBB0_72:
	s_nop 0
	global_load_dword v2, v0, s[10:11] offset:32 sc1
	s_waitcnt vmcnt(0)
	v_and_b32_e32 v2, 0xffff0000, v2
	v_cmp_ne_u32_e32 vcc, v2, v1
	s_or_b64 s[4:5], vcc, s[4:5]
	s_andn2_b64 exec, exec, s[4:5]
	s_cbranch_execnz .LBB0_72

; DI unsigned xb_ld(unsigned* p)              { return __hip_atomic_load(p, __ATOMIC_RELAXED, __HIP_MEMORY_SCOPE_AGENT); }
; DI void xcd_barrier_complete(unsigned* bar, unsigned x, unsigned& nloc, unsigned& nx) {
;     const unsigned G = gridDim.x * gridDim.y * gridDim.z;
;     unsigned sum, cnt, mine, sp = 0u;
;     for (;;) {
;         sum = 0u; cnt = 0u; mine = 0u;
; #pragma unroll
;         for (unsigned j = 0; j < 16; ++j) { const unsigned c = xb_ld(&bar[XB_XCNT(j)]); sum += c; cnt += (c > 0u) ? 1u : 0u; mine = (j == x) ? c : mine; }
;         if (sum == G) break;
;         __builtin_amdgcn_s_sleep(1);
;         if ((++sp & 255u) == 0u) { if (xb_ld(&bar[XB_TMO])) break; if (sp > XB_SPIN_CAP) { atomicAdd(&bar[XB_TMO], 1u); break; } }
;     }
;     nloc = mine > 0u ? mine : 1u; nx = cnt > 0u ? cnt : 1u;
; }
.LBB0_108:
	v_readlane_b32 s6, v255, 7
	v_readlane_b32 s7, v255, 8
	s_waitcnt lgkmcnt(0)
	global_load_dword v0, v213, s[72:73] sc1
	s_nop 2
	global_load_dword v1, v213, s[6:7] sc1
	global_load_dword v2, v213, s[92:93] sc1
	global_load_dword v3, v213, s[94:95] sc1
	v_readlane_b32 s6, v253, 8
	v_readlane_b32 s7, v253, 9
	v_readlane_b32 s14, v253, 7
	s_waitcnt vmcnt(2)
	v_add_u32_e32 v16, v1, v0
	s_nop 1
	global_load_dword v4, v213, s[6:7] sc1
	v_readlane_b32 s6, v253, 10
	v_readlane_b32 s7, v253, 11
	s_waitcnt vmcnt(2)
	v_add_u32_e32 v16, v16, v2
	s_waitcnt vmcnt(1)
	v_add_u32_e32 v16, v16, v3
	s_waitcnt vmcnt(0)
	v_add_u32_e32 v16, v16, v4
	global_load_dword v5, v213, s[6:7] sc1
	v_readlane_b32 s6, v253, 12
	v_readlane_b32 s7, v253, 13
	s_waitcnt vmcnt(0)
	v_add_u32_e32 v16, v16, v5
	s_nop 2
	global_load_dword v6, v213, s[6:7] sc1
	v_readlane_b32 s6, v253, 14
	v_readlane_b32 s7, v253, 15
	s_waitcnt vmcnt(0)
	v_add_u32_e32 v16, v16, v6
	s_nop 2
	global_load_dword v7, v213, s[6:7] sc1
	v_readlane_b32 s6, v253, 16
	v_readlane_b32 s7, v253, 17
	s_waitcnt vmcnt(0)
	v_add_u32_e32 v16, v16, v7
	s_nop 2
	global_load_dword v8, v213, s[6:7] sc1
	v_readlane_b32 s6, v253, 18
	v_readlane_b32 s7, v253, 19
	s_waitcnt vmcnt(0)
	v_add_u32_e32 v16, v16, v8
	s_nop 2
	global_load_dword v9, v213, s[6:7] sc1
	v_readlane_b32 s6, v253, 20
	v_readlane_b32 s7, v253, 21
	s_waitcnt vmcnt(0)
	v_add_u32_e32 v16, v16, v9
	s_nop 2
	global_load_dword v10, v213, s[6:7] sc1
	v_readlane_b32 s6, v253, 22
	v_readlane_b32 s7, v253, 23
	s_waitcnt vmcnt(0)
	v_add_u32_e32 v16, v16, v10
	s_nop 2
	global_load_dword v11, v213, s[6:7] sc1
	v_readlane_b32 s6, v253, 24
	v_readlane_b32 s7, v253, 25
	s_waitcnt vmcnt(0)
	v_add_u32_e32 v16, v16, v11
	s_nop 2
	global_load_dword v12, v213, s[6:7] sc1
	v_readlane_b32 s6, v253, 26
	v_readlane_b32 s7, v253, 27
	s_waitcnt vmcnt(0)
	v_add_u32_e32 v16, v16, v12
	s_nop 2
	global_load_dword v13, v213, s[6:7] sc1
	v_readlane_b32 s6, v253, 28
	v_readlane_b32 s7, v253, 29
	s_waitcnt vmcnt(0)
	v_add_u32_e32 v16, v16, v13
	s_nop 2
	global_load_dword v14, v213, s[6:7] sc1
	v_readlane_b32 s6, v253, 30
	v_readlane_b32 s7, v253, 31
	s_waitcnt vmcnt(0)
	v_add_u32_e32 v16, v16, v14
	s_nop 2
	global_load_dword v15, v213, s[6:7] sc1
	s_mov_b64 s[6:7], -1
	s_waitcnt vmcnt(0)
	v_add_u32_e32 v16, v16, v15
	v_cmp_eq_u32_e32 vcc, s14, v16
	s_mov_b64 s[14:15], -1
	s_cbranch_vccnz .LBB0_107
	s_and_b32 s6, s22, 0xff
	s_cmp_eq_u32 s6, 0
	s_mov_b64 s[6:7], -1
	s_mov_b64 s[18:19], -1
	s_nop 0
	s_cbranch_scc0 .LBB0_112
	global_load_dword v16, v213, s[86:87] sc1
	s_waitcnt vmcnt(0)
	v_cmp_eq_u32_e32 vcc, 0, v16
	s_cbranch_vccnz .LBB0_114
	s_mov_b64 s[18:19], 0

; DI unsigned xb_ld(unsigned* p)              { return __hip_atomic_load(p, __ATOMIC_RELAXED, __HIP_MEMORY_SCOPE_AGENT); }
; DI unsigned xb_add(unsigned* p, unsigned v) { return __hip_atomic_fetch_add(p, v, __ATOMIC_RELAXED, __HIP_MEMORY_SCOPE_AGENT); }
; #define XB_SPIN(cond, bar) do { unsigned _sp = 0; while (cond) { __builtin_amdgcn_s_sleep(1); \
;     if ((++_sp & 255u) == 0u) { if (xb_ld(&(bar)[XB_TMO])) break; if (_sp > XB_SPIN_CAP) { atomicAdd(&(bar)[XB_TMO], 1u); break; } } } } while (0)
; DI void xcd_barrier(const XcdBarrier& b) {
;     ...
;             const unsigned og = xb_add(&bar[XB_TOP], 1u);
;             const unsigned tg = og / nx;
;             if (og + 1u == (tg + 1u) * nx) xb_add(&bar[XB_TOPGEN], 1u);
;             else XB_SPIN(xb_ld(&bar[XB_TOPGEN]) == tg, bar);
;             __builtin_amdgcn_fence(__ATOMIC_ACQUIRE, "agent");
;             xb_add(&bar[XB_XGEN(b.x)], 1u);
;             asm volatile("s_waitcnt vmcnt(0)" ::: "memory");
;         } else {
;             XB_SPIN(xb_ld(&bar[XB_XGEN(b.x)]) == gen, bar);
.LBB0_126:
	s_and_b32 s30, s38, 0xff
	s_mov_b64 s[26:27], -1
	s_cmp_lg_u32 s30, 0
	s_mov_b64 s[36:37], -1
	s_nop 0
	s_cbranch_scc1 .LBB0_129
	global_load_dword v0, v213, s[86:87] sc1
	s_waitcnt vmcnt(0)
	v_cmp_eq_u32_e32 vcc, 0, v0
	s_cbranch_vccnz .LBB0_131
	s_mov_b64 s[36:37], 0
	s_mov_b64 s[30:31], -1
